# P1|P2 grid barrier replaced by a panel-team seam: P2 units remapped so each team prepares its own row panel; waits only for own team + previous panel's team (halo); global arrival guard before B_n sto
# speedup vs baseline: 1.0075x; 1.0075x over previous
; __device__ __forceinline__ unsigned xb_ld(unsigned* p)              { return __hip_atomic_load(p, __ATOMIC_RELAXED, __HIP_MEMORY_SCOPE_AGENT); }
; __device__ __forceinline__ unsigned xb_add(unsigned* p, unsigned v) { return __hip_atomic_fetch_add(p, v, __ATOMIC_RELAXED, __HIP_MEMORY_SCOPE_AGENT); }
; #define XB_SPIN(cond, bar) do { unsigned _sp = 0; while (cond) { __builtin_amdgcn_s_sleep(1); \
;     if ((++_sp & 255u) == 0u) { if (xb_ld(&(bar)[XB_TMO])) break; if (_sp > XB_SPIN_CAP) { atomicAdd(&(bar)[XB_TMO], 1u); break; } } } } while (0)
; #define BOTH(k) (IN(k) && (k) + 1 < hi)
; #define GRID_BAR() xcd_barrier(bar)
; __device__ __forceinline__ void xcd_barrier(const XcdBarrier& b) {
;     asm volatile("s_waitcnt vmcnt(0)" ::: "memory");
;     __syncthreads();
;     if (threadIdx.x == 0) {
;         unsigned* bar = b.bar;
;         __builtin_amdgcn_s_waitcnt(0);
;         unsigned nloc = b.st[0], nx = b.st[1];
;         if (nloc == 0u) { xcd_barrier_complete(bar, b.x, nloc, nx); b.st[0] = nloc; b.st[1] = nx; }
;         const unsigned old = xb_add(&bar[XB_XSUB(b.x)], 1u);
;         asm volatile("buffer_inv sc1" ::: "memory");
;         const unsigned gen = old / nloc;
;         if (old + 1u == (gen + 1u) * nloc) {
;             __builtin_amdgcn_fence(__ATOMIC_RELEASE, "agent");
;             asm volatile("s_waitcnt vmcnt(0)" ::: "memory");
;             const unsigned og = xb_add(&bar[XB_TOP], 1u);
;             const unsigned tg = og / nx;
;             if (og + 1u == (tg + 1u) * nx) xb_add(&bar[XB_TOPGEN], 1u);
;             else XB_SPIN(xb_ld(&bar[XB_TOPGEN]) == tg, bar);
;             asm volatile("" ::: "memory");
;             xb_add(&bar[XB_XGEN(b.x)], 1u);
;             asm volatile("s_waitcnt vmcnt(0)" ::: "memory");
;         } else {
;             XB_SPIN(xb_ld(&bar[XB_XGEN(b.x)]) == gen, bar);
;             asm volatile("s_waitcnt vmcnt(0)" ::: "memory");
;         }
;     }
;     __syncthreads();
; __global__ void __launch_bounds__(NWAVES * 64, 2) fwd(Args args) {
;     ...
;         if (BOTH(1)) GRID_BAR();
.LBB0_262:
	v_readlane_b32 s96, v240, 4
	s_cmp_lt_i32 s57, 3
	v_readlane_b32 s97, v240, 5
	s_cbranch_scc1 .LBB0_312
	s_and_saveexec_b64 s[6:7], s[96:97]
	s_cbranch_execz .Lts1_a
	s_and_b32 s3, s2, 63
	s_lshl_b32 s3, s3, 2
	s_add_u32 s8, s60, s3
	s_addc_u32 s9, s61, 0
	s_and_b32 s4, s2, 7
	s_lshl_b32 s4, s4, 3
	s_bfe_u32 s10, s2, 0x30003
	s_or_b32 s4, s4, s10
	s_add_i32 s10, s4, 1
	s_min_u32 s10, s10, 63
	s_lshr_b32 s11, s10, 3
	s_and_b32 s10, s10, 7
	s_lshl_b32 s10, s10, 3
	s_or_b32 s10, s10, s11
	s_lshl_b32 s10, s10, 2
	s_add_u32 s10, s60, s10
	s_addc_u32 s11, s61, 0
	v_mov_b32_e32 v1, 0x28000
	global_load_dword v2, v1, s[8:9] sc1
	global_load_dword v3, v1, s[8:9] offset:256 sc1
	global_load_dword v4, v1, s[8:9] offset:512 sc1
	global_load_dword v5, v1, s[8:9] offset:768 sc1
	global_load_dword v6, v1, s[10:11] sc1
	global_load_dword v7, v1, s[10:11] offset:256 sc1
	global_load_dword v8, v1, s[10:11] offset:512 sc1
	global_load_dword v9, v1, s[10:11] offset:768 sc1
.Lts1_a:
	s_or_b64 exec, exec, s[6:7]
	s_waitcnt vmcnt(0)
	s_barrier
	s_and_saveexec_b64 s[6:7], s[96:97]
	s_cbranch_execz .Lts1_join
	s_add_i32 s3, s90, 1
	v_xor_b32_e32 v2, s3, v2
	v_xor_b32_e32 v3, s3, v3
	v_xor_b32_e32 v4, s3, v4
	v_xor_b32_e32 v5, s3, v5
	v_xor_b32_e32 v6, s3, v6
	v_xor_b32_e32 v7, s3, v7
	v_xor_b32_e32 v8, s3, v8
	v_xor_b32_e32 v9, s3, v9
	v_or3_b32 v2, v2, v3, v4
	v_or3_b32 v5, v5, v6, v7
	v_or3_b32 v2, v2, v5, v8
	v_or_b32_e32 v2, v2, v9
	v_cmp_ne_u32_e32 vcc, 0, v2
	s_cbranch_vccz .Lts1_nowb
	buffer_wbl2 sc1
	s_waitcnt vmcnt(0)
.Lts1_nowb:
	s_lshl_b32 s3, s4, 7
	s_add_u32 s8, s60, s3
	s_addc_u32 s9, s61, 0
	s_add_u32 s8, s8, 0x2a000
	s_addc_u32 s9, s9, 0
	s_add_i32 s3, s4, -1
	s_max_i32 s3, s3, 0
	s_lshl_b32 s3, s3, 7
	s_add_u32 s10, s60, s3
	s_addc_u32 s11, s61, 0
	s_add_u32 s10, s10, 0x2a000
	s_addc_u32 s11, s11, 0
	v_mov_b32_e32 v1, 0
	v_mov_b32_e32 v2, 1
	v_mov_b32_e32 v3, 0x2c000
	v_mov_b32_e32 v5, 0
	global_atomic_add v1, v2, s[8:9]
	global_atomic_add v3, v2, s[60:61]
.Lts1_spin:
	global_load_dword v6, v1, s[8:9] sc1
	global_load_dword v7, v1, s[10:11] sc1
	s_waitcnt vmcnt(0)
	v_min_u32_e32 v6, v6, v7
	v_cmp_lt_u32_e32 vcc, 3, v6
	s_cbranch_vccnz .Lts1_done
	s_sleep 1
	v_add_u32_e32 v5, 1, v5
	v_cmp_gt_u32_e32 vcc, 0x4000, v5
	s_cbranch_vccnz .Lts1_spin
	global_atomic_add v1, v2, s[58:59] offset:512
.Lts1_done:
	buffer_inv sc1
	s_waitcnt vmcnt(0)

; #define LAS __attribute__((address_space(3)))
; __device__ __forceinline__ unsigned long long rt() { return __builtin_amdgcn_s_memrealtime(); }
; __global__ void __launch_bounds__(NWAVES * 64, 2) fwd(Args args) {
;     ...
;         if (tid == 0) MISC[10] = (whole && __hip_atomic_load((unsigned*)(ctl + CW_NONLOCAL), RLX_AGENT) == 0u) ? 1u : 0u;
;         __syncthreads();
;         if (PROBE_AMP == 1) { __syncthreads(); const unsigned long long t1_ = rt(); while (rt() - t1_ < t1_ - amp_t0_1) __builtin_amdgcn_s_sleep(8); __syncthreads(); }
;     }
;     if (IN(2)) {
;         const unsigned long long amp_t0_2 = (PROBE_AMP == 2 || PROBE_AMP == 21) ? rt() : 0ull;
;         {
;             { const int h_ = (int)blockIdx.x & 3; LAS float* cw = (LAS float*)(lds + CONVW_OFF);
;               for (int i = tid; i < 1536; i += NWAVES * 64) { const int part = i >> 9, j = (i >> 7) & 3, cc = i & 127; cw[i] = args.in[3][j * 1536 + part * 512 + h_ * 128 + cc]; } }
;             DnRaw R; dn_load_raw(R, (int)blockIdx.x, DNR, HALO, GBT, tid);
;             { HgRaw H; hg_load_raw(H, HGR + (size_t)blockIdx.x * 32768, tid);
;               for (int u = (int)blockIdx.x; u < 1024; u += G) p2_hg_unit(lds, HGR + (size_t)u * 32768, OLH + (size_t)u * 8192, DEC + (size_t)u * 128, tid, lane, wave, H, (u + G < 1024) ? HGR + (size_t)(u + G) * 32768 : nullptr); }
.LBB0_312:
.LBB0_317:
	s_cmp_lt_i32 s56, 3
	s_cselect_b64 s[6:7], -1, 0
	s_cmp_gt_i32 s57, 2
	s_cselect_b64 s[8:9], -1, 0
	s_and_b64 s[6:7], s[6:7], s[8:9]
	s_andn2_b64 vcc, exec, s[6:7]
	s_cbranch_vccnz .LBB0_660
	v_writelane_b32 v240, s2, 40
	v_writelane_b32 v240, s34, 41
	s_and_b32 s3, s2, 7
	s_lshl_b32 s3, s3, 3
	s_bfe_u32 s4, s2, 0x30003
	s_or_b32 s3, s3, s4
	s_lshl_b32 s3, s3, 4
	s_lshr_b32 s4, s2, 6
	s_or_b32 s2, s3, s4
	s_or_b32 s98, s2, 15
	s_mov_b32 s34, 4
	s_lshl_b32 s3, s2, 7
	v_lshrrev_b32_e32 v2, 7, v0
	s_and_b32 s3, s3, 0x180
	v_and_b32_e32 v1, 0x7f, v0
	v_mul_u32_u24_e32 v2, 0x600, v2
	v_or3_b32 v1, v2, s3, v1
	s_mov_b32 s3, 0
	v_add_u32_e32 v4, 0x21000, v184
	s_mov_b64 s[6:7], 0
	v_mov_b32_e32 v3, 0
	s_movk_i32 s4, 0x3ff

; __device__ __forceinline__ unsigned long long rt() { return __builtin_amdgcn_s_memrealtime(); }
; __global__ void __launch_bounds__(NWAVES * 64, 2) fwd(Args args) {
;     ...
;               for (int u = (int)blockIdx.x; u < 1024; u += G) p2_hg_unit(lds, HGR + (size_t)u * 32768, OLH + (size_t)u * 8192, DEC + (size_t)u * 128, tid, lane, wave, H, (u + G < 1024) ? HGR + (size_t)(u + G) * 32768 : nullptr); }
;             if (PROBE_AMP == 21) { __syncthreads(); const unsigned long long t1_ = rt(); while (rt() - t1_ < t1_ - amp_t0_2) __builtin_amdgcn_s_sleep(8); __syncthreads(); }
;             const unsigned long long amp_t1_2 = (PROBE_AMP == 22) ? rt() : 0ull;
;             for (int u = (int)blockIdx.x; u < 1024; u += G) p2_dn_unit(lds, u, DNR, HALO, args.in[3], GBT, OLD, DEC + 1024 * 128, BNB, tid, lane, wave, R, (u + G < 1024) ? u + G : -1);
.LBB0_403:
	v_readlane_b32 s2, v240, 40
	v_readlane_b32 s34, v240, 41
	s_nop 0
	s_cmp_gt_i32 s57, 3
	s_cbranch_scc1 .LBB0_611
	s_branch .LBB0_660

; #define GAS __attribute__((address_space(1)))
; #define LAS __attribute__((address_space(3)))
; #define LDS_BAR() do { asm volatile("s_waitcnt lgkmcnt(0)" ::: "memory"); __builtin_amdgcn_s_barrier(); asm volatile("" ::: "memory"); } while (0)
; __device__ __forceinline__ void p2_hg_unit(LAS unsigned char* lds, bf16_t* region, bf16_t* oloc, float* dec, int tid_in, int lane_in, int wave_in, HgRaw& R, const bf16_t* next_region, const bool ST = true) {
;     ...
;     for (int e = 0; e < 2; ++e) { const int idx = wave * 2 + e, si = idx >> 2, tj = idx & 3;
;         f32x4 acc = (f32x4){0.f, 0.f, 0.f, 0.f};
;         if (si <= tj) acc = mma_nt<128>(KT + si * 16 * 136, 136, QT + tj * 16 * 136, 136, acc, r, g);
;         const int t = 16 * tj + r, s0 = 16 * si + 4 * g;
; #pragma unroll
;         for (int i = 0; i < 4; ++i) acc[i] = (s0 + i <= t) ? acc[i] : 0.f;
;         *(LAS u64_t*)(PP + t * 72 + s0) = pack4(acc); }
; #pragma unroll
;     for (int e = 0; e < 2; ++e) { const int id = tid + 512 * e, mt = id >> 8, kb = (id >> 6) & 3, l = id & 63, r_ = l & 15, g_ = l >> 4;
;         const LAS bf16_t* src = QT + (16 * mt + r_) * 136 + 32 * kb + 4 * g_;
;         const u64_t lo = *(const LAS u64_t*)src, hi = *(const LAS u64_t*)(src + 16);
;         if (ST) *(GAS v4u*)(region + (size_t)id * 8) = (v4u){(unsigned)lo, (unsigned)(lo >> 32), (unsigned)hi, (unsigned)(hi >> 32)}; }
;     LDS_BAR();
; #pragma unroll
;     for (int e = 0; e < 4; ++e) { const int tile = wave * 4 + e, ti = tile >> 3, vj = tile & 7;
;         f32x4 acc = (f32x4){0.f, 0.f, 0.f, 0.f};
;         acc = mma_nt<64>(VT + vj * 16 * 72, 72, PP + ti * 16 * 72, 72, acc, r, g);
;         if (ST) *(GAS u64_t*)(oloc + (size_t)((vj * 4 + ti) * 64 + lane) * 4) = pack4(acc); }
; #pragma unroll
;     for (int e = 0; e < 4; ++e) { const int vj = 4 * (wave & 1) + e, kb = wave >> 1; f32x4 a0 = (f32x4){0.f, 0.f, 0.f, 0.f}, a1 = a0;
;         a0 = mma_nt<64>(KH + (2 * kb) * 16 * 72, 72, VT + vj * 16 * 72, 72, a0, r, g);
;         a1 = mma_nt<64>(KH + (2 * kb + 1) * 16 * 72, 72, VT + vj * 16 * 72, 72, a1, r, g);
;         const u64_t lo = pack4(a0), hi = pack4(a1);
;         if (ST) *(GAS v4u*)(region + 8192 + (size_t)((vj * 4 + kb) * 64 + lane) * 8) = (v4u){(unsigned)lo, (unsigned)(lo >> 32), (unsigned)hi, (unsigned)(hi >> 32)}; }
.LBB0_406:
	v_lshl_or_b32 v93, s48, 4, v1
	v_cmp_le_i32_e32 vcc, v98, v93
	v_lshlrev_b32_e32 v95, 3, v99
	v_lshlrev_b32_e32 v112, 1, v95
	s_nop 2
	v_cndmask_b32_e32 v88, 0, v88, vcc
	v_cmp_lt_i32_e32 vcc, v98, v93
	s_nop 1
	v_cndmask_b32_e32 v89, 0, v89, vcc
	v_cmp_le_i32_e32 vcc, v100, v93
	v_cvt_pk_bf16_f32 v88, v88, v89
	s_nop 0
	v_cndmask_b32_e32 v90, 0, v90, vcc
	v_cmp_le_i32_e32 vcc, v92, v93
	s_nop 1
	v_cndmask_b32_e32 v91, 0, v91, vcc
	v_cvt_pk_bf16_f32 v89, v90, v91
	v_mad_u32_u24 v90, v93, s70, v97
	ds_write_b64 v90, v[88:89]
	v_lshrrev_b32_e32 v88, 1, v114
	v_and_b32_e32 v89, 0xc0, v114
	v_and_b32_e32 v88, 24, v88
	v_add3_u32 v92, 0, v89, v88
	v_and_or_b32 v88, v115, s71, v1
	v_mad_u64_u32 v[88:89], s[48:49], v88, s69, v[92:93]
	ds_read2_b64 v[88:91], v88 offset1:4
	s_add_u32 s48, s60, s10
	v_ashrrev_i32_e32 v115, 31, v114
	s_addc_u32 s49, s61, s11
	v_lshl_add_u64 v[96:97], v[114:115], 4, s[48:49]
	v_add_co_u32_e32 v96, vcc, s72, v96
	s_lshl_b32 s41, s41, 2
	s_nop 0
	v_addc_co_u32_e32 v97, vcc, 0, v97, vcc
	s_waitcnt lgkmcnt(0)
	global_store_dwordx4 v[96:97], v[88:91], off
	v_add_u32_e32 v96, 0x200, v114
	v_ashrrev_i32_e32 v97, 31, v96
	v_lshrrev_b32_e32 v88, 4, v96
	v_and_or_b32 v88, v88, s71, v1
	v_mad_u64_u32 v[88:89], s[50:51], v88, s69, v[92:93]
	ds_read2_b64 v[88:91], v88 offset1:4
	v_lshl_add_u64 v[92:93], v[96:97], 4, s[48:49]
	v_add_co_u32_e32 v92, vcc, s72, v92
	s_and_b32 s41, s41, 4
	s_nop 0
	v_addc_co_u32_e32 v93, vcc, 0, v93, vcc
	s_waitcnt lgkmcnt(0)
	global_store_dwordx4 v[92:93], v[88:91], off
	s_mul_i32 s50, s4, 0x900
	s_add_i32 s50, s50, 0
	v_lshlrev_b32_e32 v88, 7, v1
	v_sub_u32_e32 v88, v94, v88
	v_add_u32_e32 v115, v88, v112
	s_mul_i32 s79, s41, 0x900
	s_waitcnt lgkmcnt(0)
	s_barrier
	s_add_i32 s50, s50, 0x11800
	v_add_u32_e32 v92, s79, v115
	v_mul_u32_u24_e32 v1, 0x90, v1
	ds_read_b128 v[88:91], v92 offset:53248
	v_add3_u32 v100, s50, v1, v112
	s_add_u32 s50, s60, s74
	s_addc_u32 s51, s61, s75
	s_add_i32 s80, s79, 0x900
	v_add_u32_e32 v116, s80, v115
	s_add_i32 s80, s79, 0x1200
	v_add_u32_e32 v128, s80, v115
	ds_read_b128 v[92:95], v92 offset:53312
	ds_read_b128 v[96:99], v100
	ds_read_b128 v[100:103], v100 offset:64
	ds_read_b128 v[108:111], v116 offset:53248
	ds_read_b128 v[116:119], v116 offset:53312
	ds_read_b128 v[124:127], v128 offset:53248
	s_addk_i32 s79, 0x1b00
	v_add_u32_e32 v140, s79, v115
	ds_read_b128 v[136:139], v140 offset:53248
	ds_read_b128 v[128:131], v128 offset:53312
	s_waitcnt lgkmcnt(6)
	v_mfma_f32_16x16x32_bf16 v[104:107], v[88:91], v[96:99], 0
	v_and_b32_e32 v114, 63, v114
	v_lshl_or_b32 v144, s4, 6, v114
	s_mulk_i32 s4, 0x1200
	s_waitcnt lgkmcnt(5)
	v_mfma_f32_16x16x32_bf16 v[104:107], v[92:95], v[100:103], v[104:107]
	v_lshl_add_u32 v152, s41, 8, v144
	s_add_i32 s4, s4, 0
	v_ashrrev_i32_e32 v153, 31, v152
	s_waitcnt lgkmcnt(2)
	v_mfma_f32_16x16x32_bf16 v[132:135], v[124:127], v[96:99], 0
	v_add3_u32 v1, s4, v1, v112
	s_nop 1
	v_cvt_pk_bf16_f32 v114, v104, v105
	v_cvt_pk_bf16_f32 v115, v106, v107
	s_waitcnt lgkmcnt(0)
	v_mfma_f32_16x16x32_bf16 v[104:107], v[128:131], v[100:103], v[132:135]
	ds_read_b128 v[144:147], v1 offset:34880
	v_add_u32_e32 v154, 0x100, v152
	v_ashrrev_i32_e32 v155, 31, v154
	ds_read_b128 v[132:135], v140 offset:53312
	v_mfma_f32_16x16x32_bf16 v[120:123], v[108:111], v[96:99], 0
	ds_read_b128 v[140:143], v1 offset:34816
	v_lshl_add_u64 v[156:157], v[154:155], 3, s[50:51]
	s_nop 0
	v_cvt_pk_bf16_f32 v104, v104, v105
	v_mfma_f32_16x16x32_bf16 v[96:99], v[136:139], v[96:99], 0
	v_cvt_pk_bf16_f32 v105, v106, v107
	s_add_u32 s46, s46, s22
	s_addc_u32 s47, s47, s23
	v_mfma_f32_16x16x32_bf16 v[120:123], v[116:119], v[100:103], v[120:123]
	s_add_u32 s74, s74, s36
	s_addc_u32 s75, s75, s37
	s_add_u32 s10, s10, s38
	s_waitcnt lgkmcnt(1)
	v_mfma_f32_16x16x32_bf16 v[96:99], v[132:135], v[100:103], v[96:99]
	v_lshl_add_u64 v[100:101], v[152:153], 3, s[50:51]
	global_store_dwordx2 v[100:101], v[114:115], off
	ds_read_b128 v[100:103], v1 offset:37120
	v_cvt_pk_bf16_f32 v114, v120, v121
	v_cvt_pk_bf16_f32 v115, v122, v123
	ds_read_b128 v[120:123], v1 offset:37184
	s_waitcnt lgkmcnt(2)
	v_mfma_f32_16x16x32_bf16 v[148:151], v[140:143], v[88:91], 0
	global_store_dwordx2 v[156:157], v[114:115], off
	v_add_u32_e32 v114, 0x200, v152
	v_ashrrev_i32_e32 v115, 31, v114
	s_waitcnt lgkmcnt(1)
; #define GAS __attribute__((address_space(1)))
; __device__ __forceinline__ u64_t pack4(const f32x4 v) { return (u64_t)pk2(v[0], v[1]) | ((u64_t)pk2(v[2], v[3]) << 32); }
; __device__ __forceinline__ void hg_load_raw(HgRaw& R, const bf16_t* region, int tid) {
;     const int cg = tid & 15, t0 = 2 * (tid >> 4);
; #pragma unroll
;     for (int part = 0; part < 3; ++part)
; #pragma unroll
;         for (int rr = 0; rr < 2; ++rr) R.w[part][rr] = *(const GAS v4u*)(region + part * 8192 + (t0 + rr) * 128 + 8 * cg);
; }
; __device__ __forceinline__ void p2_hg_unit(LAS unsigned char* lds, bf16_t* region, bf16_t* oloc, float* dec, int tid_in, int lane_in, int wave_in, HgRaw& R, const bf16_t* next_region, const bool ST = true) {
;     ...
;     for (int e = 0; e < 4; ++e) { const int tile = wave * 4 + e, ti = tile >> 3, vj = tile & 7;
;         f32x4 acc = (f32x4){0.f, 0.f, 0.f, 0.f};
;         acc = mma_nt<64>(VT + vj * 16 * 72, 72, PP + ti * 16 * 72, 72, acc, r, g);
;         if (ST) *(GAS u64_t*)(oloc + (size_t)((vj * 4 + ti) * 64 + lane) * 4) = pack4(acc); }
; #pragma unroll
;     for (int e = 0; e < 4; ++e) { const int vj = 4 * (wave & 1) + e, kb = wave >> 1; f32x4 a0 = (f32x4){0.f, 0.f, 0.f, 0.f}, a1 = a0;
;         a0 = mma_nt<64>(KH + (2 * kb) * 16 * 72, 72, VT + vj * 16 * 72, 72, a0, r, g);
;         a1 = mma_nt<64>(KH + (2 * kb + 1) * 16 * 72, 72, VT + vj * 16 * 72, 72, a1, r, g);
;         const u64_t lo = pack4(a0), hi = pack4(a1);
;         if (ST) *(GAS v4u*)(region + 8192 + (size_t)((vj * 4 + kb) * 64 + lane) * 8) = (v4u){(unsigned)lo, (unsigned)(lo >> 32), (unsigned)hi, (unsigned)(hi >> 32)}; }
	v_mfma_f32_16x16x32_bf16 v[88:91], v[100:103], v[88:91], 0
	v_lshl_add_u64 v[106:107], v[114:115], 3, s[50:51]
	global_store_dwordx2 v[106:107], v[104:105], off
	v_cvt_pk_bf16_f32 v104, v96, v97
	v_mfma_f32_16x16x32_bf16 v[148:151], v[144:147], v[92:95], v[148:151]
	v_cvt_pk_bf16_f32 v105, v98, v99
	v_add_u32_e32 v156, 0x300, v152
	v_ashrrev_i32_e32 v157, 31, v156
	s_waitcnt lgkmcnt(0)
	v_mfma_f32_16x16x32_bf16 v[88:91], v[120:123], v[92:95], v[88:91]
	v_lshl_add_u64 v[106:107], v[156:157], 3, s[50:51]
	global_store_dwordx2 v[106:107], v[104:105], off
	s_nop 0
	v_cvt_pk_bf16_f32 v104, v148, v149
	v_mfma_f32_16x16x32_bf16 v[92:95], v[140:143], v[108:111], 0
	v_cvt_pk_bf16_f32 v105, v150, v151
	s_nop 1
	v_cvt_pk_bf16_f32 v106, v88, v89
	v_cvt_pk_bf16_f32 v107, v90, v91
	v_mfma_f32_16x16x32_bf16 v[96:99], v[100:103], v[108:111], 0
	v_lshl_add_u64 v[108:109], v[152:153], 4, s[48:49]
	v_add_co_u32_e32 v108, vcc, s73, v108
	v_mfma_f32_16x16x32_bf16 v[92:95], v[144:147], v[116:119], v[92:95]
	s_nop 0
	v_addc_co_u32_e32 v109, vcc, 0, v109, vcc
	global_store_dwordx4 v[108:109], v[104:107], off
	v_mfma_f32_16x16x32_bf16 v[96:99], v[120:123], v[116:119], v[96:99]
	v_lshl_add_u64 v[108:109], v[154:155], 4, s[48:49]
	s_nop 2
	v_cvt_pk_bf16_f32 v92, v92, v93
	v_cvt_pk_bf16_f32 v93, v94, v95
	v_mfma_f32_16x16x32_bf16 v[88:91], v[140:143], v[124:127], 0
	v_add_co_u32_e32 v108, vcc, s73, v108
	v_cvt_pk_bf16_f32 v94, v96, v97
	v_mfma_f32_16x16x32_bf16 v[104:107], v[100:103], v[124:127], 0
	v_cvt_pk_bf16_f32 v95, v98, v99
	v_addc_co_u32_e32 v109, vcc, 0, v109, vcc
	v_mfma_f32_16x16x32_bf16 v[88:91], v[144:147], v[128:131], v[88:91]
	global_store_dwordx4 v[108:109], v[92:95], off
	s_addc_u32 s11, s11, s39
	s_waitcnt vmcnt(11)
	v_mov_b64_e32 v[110:111], v[74:75]
	v_mfma_f32_16x16x32_bf16 v[96:99], v[120:123], v[128:131], v[104:107]
	s_cmp_gt_i32 s40, s98
	s_nop 1
	v_cvt_pk_bf16_f32 v88, v88, v89
	v_cvt_pk_bf16_f32 v89, v90, v91
	v_mfma_f32_16x16x32_bf16 v[104:107], v[140:143], v[136:139], 0
	v_mov_b64_e32 v[108:109], v[72:73]
	s_nop 0
	v_cvt_pk_bf16_f32 v90, v96, v97
	v_cvt_pk_bf16_f32 v91, v98, v99
	v_mfma_f32_16x16x32_bf16 v[96:99], v[100:103], v[136:139], 0
	v_mfma_f32_16x16x32_bf16 v[92:95], v[144:147], v[132:135], v[104:107]
	s_nop 2
	v_lshl_add_u64 v[104:105], v[114:115], 4, s[48:49]
	v_add_co_u32_e32 v100, vcc, s73, v104
	s_nop 2
	v_cvt_pk_bf16_f32 v92, v92, v93
	v_addc_co_u32_e32 v101, vcc, 0, v105, vcc
	global_store_dwordx4 v[100:101], v[88:91], off
	v_cvt_pk_bf16_f32 v93, v94, v95
	s_waitcnt vmcnt(11)
	v_mov_b64_e32 v[106:107], v[78:79]
	v_mfma_f32_16x16x32_bf16 v[88:91], v[120:123], v[132:135], v[96:99]
	v_mov_b64_e32 v[102:103], v[64:65]
	v_mov_b64_e32 v[104:105], v[76:77]
	v_mov_b64_e32 v[100:101], v[62:63]
	v_mov_b64_e32 v[98:99], v[70:71]
	v_mov_b64_e32 v[96:97], v[68:69]
	s_nop 2
	v_cvt_pk_bf16_f32 v94, v88, v89
	v_lshl_add_u64 v[88:89], v[156:157], 4, s[48:49]
	v_add_co_u32_e32 v88, vcc, s73, v88
	v_cvt_pk_bf16_f32 v95, v90, v91
	s_nop 0
	v_addc_co_u32_e32 v89, vcc, 0, v89, vcc
	global_store_dwordx4 v[88:89], v[92:95], off
	s_waitcnt lgkmcnt(0)
	s_barrier
	s_waitcnt vmcnt(10)
	v_mov_b64_e32 v[90:91], v[86:87]
	v_mov_b64_e32 v[94:95], v[82:83]
	v_mov_b64_e32 v[88:89], v[84:85]
	v_mov_b64_e32 v[92:93], v[80:81]
	s_cbranch_scc1 .LBB0_423
.LBB0_407:
	s_add_i32 s40, s40, s34
	s_cmp_gt_i32 s40, s98
	s_cselect_b64 s[48:49], -1, 0
	v_mov_b32_e32 v114, v0
	s_or_b64 s[48:49], s[48:49], s[44:45]
	s_and_b64 vcc, exec, s[48:49]
	v_readfirstlane_b32 s4, v114
	s_cbranch_vccnz .LBB0_409
	s_ashr_i32 s41, s40, 31
	s_lshl_b64 s[48:49], s[40:41], 16
	v_lshlrev_b32_e32 v1, 4, v114
	s_add_u32 s48, s26, s48
	v_and_b32_e32 v62, 0xffffff00, v1
	s_addc_u32 s49, s27, s49
	v_and_b32_e32 v112, 0xf0, v1
	v_ashrrev_i32_e32 v63, 31, v62
	v_or_b32_e32 v72, 0x80, v62
	v_lshl_add_u64 v[80:81], s[48:49], 0, v[112:113]
	v_lshlrev_b64 v[82:83], 1, v[62:63]
	v_ashrrev_i32_e32 v73, 31, v72
	v_lshl_add_u64 v[68:69], v[80:81], 0, v[82:83]
	v_lshl_add_u64 v[74:75], v[80:81], 0, s[8:9]
	v_lshlrev_b64 v[84:85], 1, v[72:73]
	v_lshl_add_u64 v[80:81], v[80:81], 0, s[6:7]
	v_lshl_add_u64 v[76:77], v[74:75], 0, v[82:83]
	v_lshl_add_u64 v[78:79], v[74:75], 0, v[84:85]
	v_lshl_add_u64 v[82:83], v[80:81], 0, v[82:83]
	v_lshl_add_u64 v[84:85], v[80:81], 0, v[84:85]
	global_load_dwordx4 v[62:65], v[68:69], off nt
	s_nop 0
	global_load_dwordx4 v[68:71], v[68:69], off offset:256 nt
	s_nop 0
	global_load_dwordx4 v[72:75], v[76:77], off nt
	s_nop 0
	global_load_dwordx4 v[76:79], v[78:79], off nt
	s_nop 0
	global_load_dwordx4 v[80:83], v[82:83], off nt
	s_nop 0
	global_load_dwordx4 v[84:87], v[84:85], off nt

; __device__ __forceinline__ unsigned long long rt() { return __builtin_amdgcn_s_memrealtime(); }
; __global__ void __launch_bounds__(NWAVES * 64, 2) fwd(Args args) {
;     ...
;             DnRaw R; dn_load_raw(R, (int)blockIdx.x, DNR, HALO, GBT, tid);
;             { HgRaw H; hg_load_raw(H, HGR + (size_t)blockIdx.x * 32768, tid);
;               for (int u = (int)blockIdx.x; u < 1024; u += G) p2_hg_unit(lds, HGR + (size_t)u * 32768, OLH + (size_t)u * 8192, DEC + (size_t)u * 128, tid, lane, wave, H, (u + G < 1024) ? HGR + (size_t)(u + G) * 32768 : nullptr); }
;             if (PROBE_AMP == 21) { __syncthreads(); const unsigned long long t1_ = rt(); while (rt() - t1_ < t1_ - amp_t0_2) __builtin_amdgcn_s_sleep(8); __syncthreads(); }
;             const unsigned long long amp_t1_2 = (PROBE_AMP == 22) ? rt() : 0ull;
;             for (int u = (int)blockIdx.x; u < 1024; u += G) p2_dn_unit(lds, u, DNR, HALO, args.in[3], GBT, OLD, DEC + 1024 * 128, BNB, tid, lane, wave, R, (u + G < 1024) ? u + G : -1);
.LBB0_423:
	s_cmpk_gt_u32 s2, 0xbf
	s_cbranch_scc1 .Lts1_gskip
	s_and_saveexec_b64 s[6:7], s[96:97]
	s_cbranch_execz .Lts1_gjoin
	v_mov_b32_e32 v68, 0x2c000
	v_mov_b32_e32 v70, 0
.Lts1_gspin:
	global_load_dword v69, v68, s[60:61] sc1
	s_waitcnt vmcnt(0)
	v_cmp_lt_u32_e32 vcc, 0xff, v69
	s_cbranch_vccnz .Lts1_gjoin
	s_sleep 1
	v_add_u32_e32 v70, 1, v70
	v_cmp_gt_u32_e32 vcc, 0x4000, v70
	s_cbranch_vccnz .Lts1_gspin
	v_mov_b32_e32 v68, 0
	v_mov_b32_e32 v69, 1
	global_atomic_add v68, v69, s[58:59] offset:512
.Lts1_gjoin:
	s_or_b64 exec, exec, s[6:7]
	s_barrier

; __device__ __forceinline__ float siluf_(float x) { return x * __builtin_amdgcn_rcpf(1.f + __expf(-x)); }
; __device__ __forceinline__ u32x4 pack8(const f32x4 a, const f32x4 b) { u32x4 w; w.x = cvt_pk_bf16(a[0], a[1]); w.y = cvt_pk_bf16(a[2], a[3]); w.z = cvt_pk_bf16(b[0], b[1]); w.w = cvt_pk_bf16(b[2], b[3]); return w; }
; #define LAS __attribute__((address_space(3)))
;     ...
; #pragma unroll
;     for (int part = 0; part < 3; ++part) {
;         f32x4 raw[5][2];
; #pragma unroll
;         for (int j = 0; j < 5; ++j) unpack8(R.w[part][j], raw[j][0], raw[j][1]);
;         f32x4 w[4][2];
; #pragma unroll
;         for (int j = 0; j < 4; ++j) { const LAS float* wp = (const LAS float*)(lds + CONVW_OFF) + (part * 4 + j) * 128 + 8 * cg; w[j][0] = *(const LAS f32x4*)wp; w[j][1] = *(const LAS f32x4*)(wp + 4); }
;         f32x4 o[2][2];
; #pragma unroll
;         for (int rr = 0; rr < 2; ++rr)
; #pragma unroll
;             for (int hh = 0; hh < 2; ++hh) { f32x4 a = w[0][hh] * raw[rr][hh] + w[1][hh] * raw[rr + 1][hh] + w[2][hh] * raw[rr + 2][hh] + w[3][hh] * raw[rr + 3][hh];
; #pragma unroll
;                 for (int i = 0; i < 4; ++i) a[i] = siluf_(a[i]);
;                 o[rr][hh] = a; }
;         if (part < 2) { LAS bf16_t* dst = part == 0 ? QN : KN;
; #pragma unroll
;             for (int rr = 0; rr < 2; ++rr) *(LAS v4u*)(dst + (t0 + rr) * 136 + 8 * cg) = pack8(o[rr][0], o[rr][1]); }
.LBB0_425:
	v_mov_b32_e32 v96, v0
	v_lshlrev_b32_e32 v110, 16, v12
	v_and_b32_e32 v94, 15, v96
	v_lshlrev_b32_e32 v95, 5, v94
	v_add_u32_e32 v64, 0, v95
	v_add_u32_e32 v65, 0x21000, v64
	ds_read_b128 v[68:71], v65
	ds_read_b128 v[74:77], v65 offset:16
	ds_read_b128 v[78:81], v65 offset:528
	ds_read_b128 v[82:85], v65 offset:512
	v_and_b32_e32 v111, 0xffff0000, v12
	v_lshlrev_b32_e32 v112, 16, v13
	v_and_b32_e32 v113, 0xffff0000, v13
	v_lshlrev_b32_e32 v106, 16, v8
	v_and_b32_e32 v107, 0xffff0000, v8
	v_lshlrev_b32_e32 v108, 16, v9
	v_and_b32_e32 v109, 0xffff0000, v9
	s_waitcnt lgkmcnt(1)
	v_pk_mul_f32 v[86:87], v[80:81], v[112:113]
	v_pk_mul_f32 v[88:89], v[78:79], v[110:111]
	v_pk_fma_f32 v[98:99], v[76:77], v[108:109], v[86:87]
	v_pk_fma_f32 v[100:101], v[74:75], v[106:107], v[88:89]
	ds_read_b128 v[86:89], v65 offset:1040
	ds_read_b128 v[90:93], v65 offset:1024
	v_lshlrev_b32_e32 v114, 16, v16
	v_and_b32_e32 v115, 0xffff0000, v16
	v_lshlrev_b32_e32 v116, 16, v17
	v_and_b32_e32 v117, 0xffff0000, v17
	s_waitcnt lgkmcnt(1)
	v_pk_fma_f32 v[118:119], v[86:87], v[114:115], v[100:101]
	v_pk_fma_f32 v[120:121], v[88:89], v[116:117], v[98:99]
	ds_read_b128 v[98:101], v65 offset:1552
	ds_read_b128 v[102:105], v65 offset:1536
	v_lshlrev_b32_e32 v130, 16, v10
	v_and_b32_e32 v131, 0xffff0000, v10
	v_lshlrev_b32_e32 v132, 16, v11
	v_and_b32_e32 v133, 0xffff0000, v11
	v_lshlrev_b32_e32 v126, 16, v6
	v_and_b32_e32 v127, 0xffff0000, v6
	v_lshlrev_b32_e32 v128, 16, v7
	v_and_b32_e32 v129, 0xffff0000, v7
	v_pk_mul_f32 v[134:135], v[84:85], v[132:133]
	v_pk_mul_f32 v[136:137], v[82:83], v[130:131]
	v_pk_fma_f32 v[134:135], v[70:71], v[128:129], v[134:135]
	v_pk_fma_f32 v[136:137], v[68:69], v[126:127], v[136:137]
	v_lshlrev_b32_e32 v138, 16, v14
	v_and_b32_e32 v139, 0xffff0000, v14
	v_lshlrev_b32_e32 v140, 16, v15
	v_and_b32_e32 v141, 0xffff0000, v15
	v_lshlrev_b32_e32 v122, 16, v20
	v_and_b32_e32 v123, 0xffff0000, v20
	v_lshlrev_b32_e32 v124, 16, v21
	v_and_b32_e32 v125, 0xffff0000, v21
	s_waitcnt lgkmcnt(2)
	v_pk_fma_f32 v[136:137], v[90:91], v[138:139], v[136:137]
	v_pk_fma_f32 v[134:135], v[92:93], v[140:141], v[134:135]
	v_lshlrev_b32_e32 v142, 16, v18
	v_and_b32_e32 v143, 0xffff0000, v18
	v_lshlrev_b32_e32 v144, 16, v19
	v_and_b32_e32 v145, 0xffff0000, v19
	s_waitcnt lgkmcnt(1)
	v_pk_fma_f32 v[118:119], v[98:99], v[122:123], v[118:119]
	v_pk_fma_f32 v[120:121], v[100:101], v[124:125], v[120:121]
	s_waitcnt lgkmcnt(0)
	v_pk_fma_f32 v[136:137], v[102:103], v[142:143], v[136:137]
	v_pk_fma_f32 v[134:135], v[104:105], v[144:145], v[134:135]
	v_mul_f32_e32 v122, 0xbfb8aa3b, v118
	v_mul_f32_e32 v123, 0xbfb8aa3b, v119
	v_mul_f32_e32 v124, 0xbfb8aa3b, v120
	v_mul_f32_e32 v125, 0xbfb8aa3b, v121
	v_mul_f32_e32 v142, 0xbfb8aa3b, v136
	v_mul_f32_e32 v143, 0xbfb8aa3b, v137
	v_mul_f32_e32 v144, 0xbfb8aa3b, v134
	v_mul_f32_e32 v145, 0xbfb8aa3b, v135
	v_exp_f32_e32 v122, v122
	v_exp_f32_e32 v123, v123
	v_exp_f32_e32 v124, v124
	v_exp_f32_e32 v125, v125
	v_exp_f32_e32 v142, v142
	v_exp_f32_e32 v143, v143
	v_exp_f32_e32 v144, v144
	v_exp_f32_e32 v145, v145
	v_add_f32_e32 v122, 1.0, v122
	v_add_f32_e32 v123, 1.0, v123
	v_add_f32_e32 v124, 1.0, v124
	v_add_f32_e32 v125, 1.0, v125
	v_add_f32_e32 v142, 1.0, v142
	v_add_f32_e32 v143, 1.0, v143
	v_add_f32_e32 v144, 1.0, v144
	v_add_f32_e32 v145, 1.0, v145
	v_rcp_f32_e32 v122, v122
	v_rcp_f32_e32 v123, v123
	v_rcp_f32_e32 v124, v124
	v_rcp_f32_e32 v125, v125
	v_rcp_f32_e32 v142, v142
	v_rcp_f32_e32 v143, v143
	v_rcp_f32_e32 v144, v144
	v_rcp_f32_e32 v145, v145
	v_pk_mul_f32 v[118:119], v[118:119], v[122:123]
	v_pk_mul_f32 v[120:121], v[120:121], v[124:125]
	v_pk_mul_f32 v[122:123], v[136:137], v[142:143]
	v_pk_mul_f32 v[124:125], v[134:135], v[144:145]
	v_lshlrev_b32_e32 v134, 16, v4
	v_and_b32_e32 v135, 0xffff0000, v4
	v_lshlrev_b32_e32 v136, 16, v5
	v_and_b32_e32 v137, 0xffff0000, v5
	v_pk_mul_f32 v[80:81], v[80:81], v[108:109]
	v_pk_mul_f32 v[78:79], v[78:79], v[106:107]
	v_pk_fma_f32 v[76:77], v[76:77], v[136:137], v[80:81]
	v_pk_fma_f32 v[74:75], v[74:75], v[134:135], v[78:79]
	v_pk_fma_f32 v[76:77], v[88:89], v[112:113], v[76:77]
	v_pk_fma_f32 v[74:75], v[86:87], v[110:111], v[74:75]
	v_lshlrev_b32_e32 v86, 16, v2
	v_and_b32_e32 v87, 0xffff0000, v2
	v_lshlrev_b32_e32 v88, 16, v3
	v_and_b32_e32 v89, 0xffff0000, v3
	v_pk_mul_f32 v[84:85], v[84:85], v[128:129]
	v_pk_mul_f32 v[82:83], v[82:83], v[126:127]
	v_pk_fma_f32 v[70:71], v[70:71], v[88:89], v[84:85]
	v_pk_fma_f32 v[68:69], v[68:69], v[86:87], v[82:83]
	v_pk_fma_f32 v[70:71], v[92:93], v[132:133], v[70:71]
	v_pk_fma_f32 v[68:69], v[90:91], v[130:131], v[68:69]
	v_pk_fma_f32 v[74:75], v[98:99], v[114:115], v[74:75]
	v_pk_fma_f32 v[68:69], v[102:103], v[138:139], v[68:69]
	v_pk_fma_f32 v[70:71], v[104:105], v[140:141], v[70:71]
	v_mul_f32_e32 v78, 0xbfb8aa3b, v74
	v_mul_f32_e32 v79, 0xbfb8aa3b, v75
	v_pk_fma_f32 v[76:77], v[100:101], v[116:117], v[76:77]
	v_mul_f32_e32 v82, 0xbfb8aa3b, v68
	v_mul_f32_e32 v83, 0xbfb8aa3b, v69
	v_mul_f32_e32 v84, 0xbfb8aa3b, v70
	v_mul_f32_e32 v85, 0xbfb8aa3b, v71
	v_exp_f32_e32 v78, v78
	v_exp_f32_e32 v79, v79
	v_mul_f32_e32 v80, 0xbfb8aa3b, v76
	v_mul_f32_e32 v81, 0xbfb8aa3b, v77
	v_exp_f32_e32 v82, v82
	v_exp_f32_e32 v83, v83
	v_exp_f32_e32 v84, v84
	v_exp_f32_e32 v85, v85
	v_exp_f32_e32 v80, v80
	v_exp_f32_e32 v81, v81
	v_add_f32_e32 v78, 1.0, v78
	v_add_f32_e32 v79, 1.0, v79
	v_add_f32_e32 v82, 1.0, v82
	v_add_f32_e32 v83, 1.0, v83
	v_add_f32_e32 v84, 1.0, v84
	v_add_f32_e32 v85, 1.0, v85
	v_rcp_f32_e32 v78, v78
	v_rcp_f32_e32 v79, v79
	v_add_f32_e32 v80, 1.0, v80
	v_add_f32_e32 v81, 1.0, v81
	v_rcp_f32_e32 v82, v82
	v_rcp_f32_e32 v83, v83
	v_rcp_f32_e32 v84, v84
	v_rcp_f32_e32 v85, v85
	v_rcp_f32_e32 v80, v80
	v_rcp_f32_e32 v81, v81
	v_ashrrev_i32_e32 v72, 3, v96
	v_and_b32_e32 v73, -2, v72
	v_lshlrev_b32_e32 v97, 4, v94
	v_pk_mul_f32 v[74:75], v[74:75], v[78:79]
	v_pk_mul_f32 v[68:69], v[68:69], v[82:83]
	v_pk_mul_f32 v[70:71], v[70:71], v[84:85]
	v_pk_mul_f32 v[76:77], v[76:77], v[80:81]
	v_add_u32_e32 v78, 0, v97
	v_cvt_pk_bf16_f32 v68, v68, v69
	v_cvt_pk_bf16_f32 v69, v70, v71
	v_cvt_pk_bf16_f32 v70, v74, v75
	v_mul_lo_u32 v75, v73, s74
	v_or_b32_e32 v74, 1, v72
	v_cvt_pk_bf16_f32 v71, v76, v77
	v_add_u32_e32 v77, v78, v75
	v_mul_lo_u32 v76, v74, s74
	v_add_u32_e32 v64, s35, v97
	ds_write_b128 v77, v[68:71] offset:17408
	v_cvt_pk_bf16_f32 v68, v122, v123
	v_cvt_pk_bf16_f32 v69, v124, v125
	v_cvt_pk_bf16_f32 v70, v118, v119
	v_cvt_pk_bf16_f32 v71, v120, v121
	v_add_u32_e32 v97, v78, v76
	ds_write_b128 v97, v[68:71] offset:17408
	ds_read_b128 v[68:71], v65 offset:2048
	ds_read_b128 v[78:81], v65 offset:2064
	ds_read_b128 v[82:85], v65 offset:2576
	ds_read_b128 v[86:89], v65 offset:2560
	v_lshlrev_b32_e32 v114, 16, v32
	v_and_b32_e32 v115, 0xffff0000, v32
	v_lshlrev_b32_e32 v116, 16, v33
	v_and_b32_e32 v117, 0xffff0000, v33
	v_lshlrev_b32_e32 v110, 16, v28
	v_and_b32_e32 v111, 0xffff0000, v28
	v_lshlrev_b32_e32 v112, 16, v29
	v_and_b32_e32 v113, 0xffff0000, v29
	s_waitcnt lgkmcnt(1)
; __device__ __forceinline__ float siluf_(float x) { return x * __builtin_amdgcn_rcpf(1.f + __expf(-x)); }
; __device__ __forceinline__ u32x4 pack8(const f32x4 a, const f32x4 b) { u32x4 w; w.x = cvt_pk_bf16(a[0], a[1]); w.y = cvt_pk_bf16(a[2], a[3]); w.z = cvt_pk_bf16(b[0], b[1]); w.w = cvt_pk_bf16(b[2], b[3]); return w; }
; #define LAS __attribute__((address_space(3)))
;     ...
; #pragma unroll
;     for (int part = 0; part < 3; ++part) {
;         f32x4 raw[5][2];
; #pragma unroll
;         for (int j = 0; j < 5; ++j) unpack8(R.w[part][j], raw[j][0], raw[j][1]);
;         f32x4 w[4][2];
; #pragma unroll
;         for (int j = 0; j < 4; ++j) { const LAS float* wp = (const LAS float*)(lds + CONVW_OFF) + (part * 4 + j) * 128 + 8 * cg; w[j][0] = *(const LAS f32x4*)wp; w[j][1] = *(const LAS f32x4*)(wp + 4); }
;         f32x4 o[2][2];
; #pragma unroll
;         for (int rr = 0; rr < 2; ++rr)
; #pragma unroll
;             for (int hh = 0; hh < 2; ++hh) { f32x4 a = w[0][hh] * raw[rr][hh] + w[1][hh] * raw[rr + 1][hh] + w[2][hh] * raw[rr + 2][hh] + w[3][hh] * raw[rr + 3][hh];
; #pragma unroll
;                 for (int i = 0; i < 4; ++i) a[i] = siluf_(a[i]);
;                 o[rr][hh] = a; }
;         if (part < 2) { LAS bf16_t* dst = part == 0 ? QN : KN;
; #pragma unroll
;             for (int rr = 0; rr < 2; ++rr) *(LAS v4u*)(dst + (t0 + rr) * 136 + 8 * cg) = pack8(o[rr][0], o[rr][1]); }
	v_pk_mul_f32 v[90:91], v[84:85], v[116:117]
	v_pk_mul_f32 v[92:93], v[82:83], v[114:115]
	v_pk_fma_f32 v[102:103], v[80:81], v[112:113], v[90:91]
	v_pk_fma_f32 v[104:105], v[78:79], v[110:111], v[92:93]
	ds_read_b128 v[90:93], v65 offset:3088
	ds_read_b128 v[98:101], v65 offset:3072
	v_lshlrev_b32_e32 v118, 16, v36
	v_and_b32_e32 v119, 0xffff0000, v36
	v_lshlrev_b32_e32 v120, 16, v37
	v_and_b32_e32 v121, 0xffff0000, v37
	s_waitcnt lgkmcnt(1)
	v_pk_fma_f32 v[122:123], v[90:91], v[118:119], v[104:105]
	v_pk_fma_f32 v[124:125], v[92:93], v[120:121], v[102:103]
	ds_read_b128 v[102:105], v65 offset:3600
	ds_read_b128 v[106:109], v65 offset:3584
	v_lshlrev_b32_e32 v134, 16, v30
	v_and_b32_e32 v135, 0xffff0000, v30
	v_lshlrev_b32_e32 v136, 16, v31
	v_and_b32_e32 v137, 0xffff0000, v31
	v_lshlrev_b32_e32 v130, 16, v26
	v_and_b32_e32 v131, 0xffff0000, v26
	v_lshlrev_b32_e32 v132, 16, v27
	v_and_b32_e32 v133, 0xffff0000, v27
	v_pk_mul_f32 v[138:139], v[88:89], v[136:137]
	v_pk_mul_f32 v[140:141], v[86:87], v[134:135]
	v_pk_fma_f32 v[138:139], v[70:71], v[132:133], v[138:139]
	v_pk_fma_f32 v[140:141], v[68:69], v[130:131], v[140:141]
	v_lshlrev_b32_e32 v142, 16, v34
	v_and_b32_e32 v143, 0xffff0000, v34
	v_lshlrev_b32_e32 v144, 16, v35
	v_and_b32_e32 v145, 0xffff0000, v35
	v_lshlrev_b32_e32 v126, 16, v40
	v_and_b32_e32 v127, 0xffff0000, v40
	v_lshlrev_b32_e32 v128, 16, v41
	v_and_b32_e32 v129, 0xffff0000, v41
	s_waitcnt lgkmcnt(2)
	v_pk_fma_f32 v[140:141], v[98:99], v[142:143], v[140:141]
	v_pk_fma_f32 v[138:139], v[100:101], v[144:145], v[138:139]
	v_lshlrev_b32_e32 v146, 16, v38
	v_and_b32_e32 v147, 0xffff0000, v38
	v_lshlrev_b32_e32 v148, 16, v39
	v_and_b32_e32 v149, 0xffff0000, v39
	s_waitcnt lgkmcnt(1)
	v_pk_fma_f32 v[122:123], v[102:103], v[126:127], v[122:123]
	v_pk_fma_f32 v[124:125], v[104:105], v[128:129], v[124:125]
	s_waitcnt lgkmcnt(0)
	v_pk_fma_f32 v[140:141], v[106:107], v[146:147], v[140:141]
	v_pk_fma_f32 v[138:139], v[108:109], v[148:149], v[138:139]
	v_mul_f32_e32 v126, 0xbfb8aa3b, v122
	v_mul_f32_e32 v127, 0xbfb8aa3b, v123
	v_mul_f32_e32 v128, 0xbfb8aa3b, v124
	v_mul_f32_e32 v129, 0xbfb8aa3b, v125
	v_mul_f32_e32 v146, 0xbfb8aa3b, v140
	v_mul_f32_e32 v147, 0xbfb8aa3b, v141
	v_mul_f32_e32 v148, 0xbfb8aa3b, v138
	v_mul_f32_e32 v149, 0xbfb8aa3b, v139
	v_exp_f32_e32 v126, v126
	v_exp_f32_e32 v127, v127
	v_exp_f32_e32 v128, v128
	v_exp_f32_e32 v129, v129
	v_exp_f32_e32 v146, v146
	v_exp_f32_e32 v147, v147
	v_exp_f32_e32 v148, v148
	v_exp_f32_e32 v149, v149
	v_add_f32_e32 v126, 1.0, v126
	v_add_f32_e32 v127, 1.0, v127
	v_add_f32_e32 v128, 1.0, v128
	v_add_f32_e32 v129, 1.0, v129
	v_add_f32_e32 v146, 1.0, v146
	v_add_f32_e32 v147, 1.0, v147
	v_add_f32_e32 v148, 1.0, v148
	v_add_f32_e32 v149, 1.0, v149
	v_rcp_f32_e32 v126, v126
	v_rcp_f32_e32 v127, v127
	v_rcp_f32_e32 v128, v128
	v_rcp_f32_e32 v129, v129
	v_rcp_f32_e32 v146, v146
	v_rcp_f32_e32 v147, v147
	v_rcp_f32_e32 v148, v148
	v_rcp_f32_e32 v149, v149
	v_pk_mul_f32 v[122:123], v[122:123], v[126:127]
	v_pk_mul_f32 v[124:125], v[124:125], v[128:129]
	v_pk_mul_f32 v[126:127], v[140:141], v[146:147]
	v_pk_mul_f32 v[128:129], v[138:139], v[148:149]
	v_lshlrev_b32_e32 v138, 16, v24
	v_and_b32_e32 v139, 0xffff0000, v24
	v_lshlrev_b32_e32 v140, 16, v25
	v_and_b32_e32 v141, 0xffff0000, v25
	v_pk_mul_f32 v[84:85], v[84:85], v[112:113]
	v_pk_mul_f32 v[82:83], v[82:83], v[110:111]
	v_pk_fma_f32 v[80:81], v[80:81], v[140:141], v[84:85]
	v_pk_fma_f32 v[78:79], v[78:79], v[138:139], v[82:83]
	v_pk_fma_f32 v[80:81], v[92:93], v[116:117], v[80:81]
	v_pk_fma_f32 v[78:79], v[90:91], v[114:115], v[78:79]
	v_lshlrev_b32_e32 v90, 16, v22
	v_and_b32_e32 v91, 0xffff0000, v22
	v_lshlrev_b32_e32 v92, 16, v23
	v_and_b32_e32 v93, 0xffff0000, v23
	v_pk_mul_f32 v[88:89], v[88:89], v[132:133]
	v_pk_mul_f32 v[86:87], v[86:87], v[130:131]
	v_pk_fma_f32 v[70:71], v[70:71], v[92:93], v[88:89]
	v_pk_fma_f32 v[68:69], v[68:69], v[90:91], v[86:87]
	v_pk_fma_f32 v[70:71], v[100:101], v[136:137], v[70:71]
	v_pk_fma_f32 v[68:69], v[98:99], v[134:135], v[68:69]
	v_pk_fma_f32 v[78:79], v[102:103], v[118:119], v[78:79]
	v_pk_fma_f32 v[80:81], v[104:105], v[120:121], v[80:81]
	v_pk_fma_f32 v[68:69], v[106:107], v[142:143], v[68:69]
	v_pk_fma_f32 v[70:71], v[108:109], v[144:145], v[70:71]
	v_mul_f32_e32 v82, 0xbfb8aa3b, v78
	v_mul_f32_e32 v83, 0xbfb8aa3b, v79
	v_mul_f32_e32 v84, 0xbfb8aa3b, v80
	v_mul_f32_e32 v85, 0xbfb8aa3b, v81
	v_mul_f32_e32 v86, 0xbfb8aa3b, v68
	v_mul_f32_e32 v87, 0xbfb8aa3b, v69
	v_mul_f32_e32 v88, 0xbfb8aa3b, v70
	v_mul_f32_e32 v89, 0xbfb8aa3b, v71
	v_exp_f32_e32 v82, v82
	v_exp_f32_e32 v83, v83
	v_exp_f32_e32 v84, v84
	v_exp_f32_e32 v85, v85
	v_exp_f32_e32 v86, v86
	v_exp_f32_e32 v87, v87
	v_exp_f32_e32 v88, v88
	v_exp_f32_e32 v89, v89
	v_add_f32_e32 v82, 1.0, v82
	v_add_f32_e32 v83, 1.0, v83
	v_add_f32_e32 v84, 1.0, v84
	v_add_f32_e32 v85, 1.0, v85
	v_add_f32_e32 v86, 1.0, v86
	v_add_f32_e32 v87, 1.0, v87
	v_add_f32_e32 v88, 1.0, v88
	v_add_f32_e32 v89, 1.0, v89
	v_rcp_f32_e32 v82, v82
	v_rcp_f32_e32 v83, v83
	v_rcp_f32_e32 v84, v84
	v_rcp_f32_e32 v85, v85
	v_rcp_f32_e32 v86, v86
	v_rcp_f32_e32 v87, v87
	v_rcp_f32_e32 v88, v88
	v_rcp_f32_e32 v89, v89
	v_pk_mul_f32 v[78:79], v[78:79], v[82:83]
	v_pk_mul_f32 v[80:81], v[80:81], v[84:85]
	v_pk_mul_f32 v[68:69], v[68:69], v[86:87]
	v_pk_mul_f32 v[70:71], v[70:71], v[88:89]
	v_cvt_pk_bf16_f32 v68, v68, v69
	v_cvt_pk_bf16_f32 v69, v70, v71
	v_cvt_pk_bf16_f32 v70, v78, v79
	v_cvt_pk_bf16_f32 v71, v80, v81
	ds_write_b128 v77, v[68:71]
	v_cvt_pk_bf16_f32 v68, v126, v127
	v_cvt_pk_bf16_f32 v69, v128, v129
	v_cvt_pk_bf16_f32 v70, v122, v123
	v_cvt_pk_bf16_f32 v71, v124, v125
	ds_write_b128 v97, v[68:71]
	ds_read_b128 v[68:71], v65 offset:4096
	ds_read_b128 v[78:81], v65 offset:4112
	ds_read_b128 v[82:85], v65 offset:4624
	ds_read_b128 v[86:89], v65 offset:4608
	v_lshlrev_b32_e32 v114, 16, v52
	v_and_b32_e32 v115, 0xffff0000, v52
	v_lshlrev_b32_e32 v116, 16, v53
	v_and_b32_e32 v117, 0xffff0000, v53
	v_lshlrev_b32_e32 v110, 16, v48
	v_and_b32_e32 v111, 0xffff0000, v48
	v_lshlrev_b32_e32 v112, 16, v49
	v_and_b32_e32 v113, 0xffff0000, v49
	s_waitcnt lgkmcnt(1)
; __device__ __forceinline__ float siluf_(float x) { return x * __builtin_amdgcn_rcpf(1.f + __expf(-x)); }
; #define GAS __attribute__((address_space(1)))
; #define LAS __attribute__((address_space(3)))
; __device__ __forceinline__ void dn_load_raw(DnRaw& R, int unit, const bf16_t* DNR, const bf16_t* HALO, const float* GBT, int tid) {
;     const bf16_t* region = DNR + (size_t)unit * 32768; const int rb = unit >> 2, h = unit & 3, n = rb & (NCH - 1), cg = tid & 15, t0 = 2 * (tid >> 4);
; #pragma unroll
;     for (int part = 0; part < 3; ++part)
; #pragma unroll
;         for (int j = 0; j < 5; ++j) { const int t = t0 - 3 + j; v4u w4 = (v4u){0u, 0u, 0u, 0u};
;             if (t >= 0) w4 = *(const GAS v4u*)(region + part * 8192 + t * 128 + 8 * cg);
;             else if (n != 0) w4 = *(const GAS v4u*)(HALO + (size_t)(rb - 1) * 4608 + (t + 3) * 1536 + h * 384 + part * 128 + 8 * cg);
;             R.w[part][j] = w4; }
;     ...
; #pragma unroll
;     for (int part = 0; part < 3; ++part) {
;         f32x4 raw[5][2];
; #pragma unroll
;         for (int j = 0; j < 5; ++j) unpack8(R.w[part][j], raw[j][0], raw[j][1]);
;         f32x4 w[4][2];
; #pragma unroll
;         for (int j = 0; j < 4; ++j) { const LAS float* wp = (const LAS float*)(lds + CONVW_OFF) + (part * 4 + j) * 128 + 8 * cg; w[j][0] = *(const LAS f32x4*)wp; w[j][1] = *(const LAS f32x4*)(wp + 4); }
;         f32x4 o[2][2];
; #pragma unroll
;         for (int rr = 0; rr < 2; ++rr)
; #pragma unroll
;             for (int hh = 0; hh < 2; ++hh) { f32x4 a = w[0][hh] * raw[rr][hh] + w[1][hh] * raw[rr + 1][hh] + w[2][hh] * raw[rr + 2][hh] + w[3][hh] * raw[rr + 3][hh];
; #pragma unroll
;                 for (int i = 0; i < 4; ++i) a[i] = siluf_(a[i]);
;                 o[rr][hh] = a; }
;         if (part < 2) { LAS bf16_t* dst = part == 0 ? QN : KN;
; #pragma unroll
;             for (int rr = 0; rr < 2; ++rr) *(LAS v4u*)(dst + (t0 + rr) * 136 + 8 * cg) = pack8(o[rr][0], o[rr][1]); }
;         if (part == 2) {
; #pragma unroll
;             for (int rr = 0; rr < 2; ++rr) *(LAS v4u*)(VR + (t0 + rr) * 136 + 8 * cg) = pack8(o[rr][0], o[rr][1]); }
;         asm volatile("" ::: "memory");
;     }
;     const float be_ = R.be; float gg_ = R.gg;
;     if (next_unit >= 0) dn_load_raw(R, next_unit, DNR, HALO, GBT, tid);
	v_pk_mul_f32 v[90:91], v[84:85], v[116:117]
	v_pk_mul_f32 v[92:93], v[82:83], v[114:115]
	v_pk_fma_f32 v[102:103], v[80:81], v[112:113], v[90:91]
	v_pk_fma_f32 v[104:105], v[78:79], v[110:111], v[92:93]
	ds_read_b128 v[90:93], v65 offset:5136
	ds_read_b128 v[98:101], v65 offset:5120
	v_lshlrev_b32_e32 v118, 16, v56
	v_and_b32_e32 v119, 0xffff0000, v56
	v_lshlrev_b32_e32 v120, 16, v57
	v_and_b32_e32 v121, 0xffff0000, v57
	s_waitcnt lgkmcnt(1)
	v_pk_fma_f32 v[122:123], v[90:91], v[118:119], v[104:105]
	v_pk_fma_f32 v[124:125], v[92:93], v[120:121], v[102:103]
	ds_read_b128 v[102:105], v65 offset:5648
	ds_read_b128 v[106:109], v65 offset:5632
	v_lshlrev_b32_e32 v126, 16, v60
	v_and_b32_e32 v127, 0xffff0000, v60
	v_lshlrev_b32_e32 v128, 16, v61
	s_waitcnt lgkmcnt(1)
	v_pk_fma_f32 v[122:123], v[102:103], v[126:127], v[122:123]
	v_and_b32_e32 v129, 0xffff0000, v61
	v_mul_f32_e32 v65, 0xbfb8aa3b, v122
	v_exp_f32_e32 v65, v65
	v_mul_f32_e32 v77, 0xbfb8aa3b, v123
	v_exp_f32_e32 v77, v77
	v_pk_fma_f32 v[124:125], v[104:105], v[128:129], v[124:125]
	v_add_f32_e32 v65, 1.0, v65
	v_rcp_f32_e32 v126, v65
	v_add_f32_e32 v65, 1.0, v77
	v_mul_f32_e32 v77, 0xbfb8aa3b, v124
	v_exp_f32_e32 v77, v77
	v_mul_f32_e32 v97, 0xbfb8aa3b, v125
	v_exp_f32_e32 v97, v97
	v_lshlrev_b32_e32 v134, 16, v50
	v_and_b32_e32 v135, 0xffff0000, v50
	v_lshlrev_b32_e32 v130, 16, v46
	v_and_b32_e32 v131, 0xffff0000, v46
	v_pk_mul_f32 v[140:141], v[86:87], v[134:135]
	v_lshlrev_b32_e32 v142, 16, v54
	v_pk_fma_f32 v[140:141], v[68:69], v[130:131], v[140:141]
	v_and_b32_e32 v143, 0xffff0000, v54
	v_rcp_f32_e32 v127, v65
	v_add_f32_e32 v65, 1.0, v77
	v_pk_fma_f32 v[140:141], v[98:99], v[142:143], v[140:141]
	v_lshlrev_b32_e32 v146, 16, v58
	v_and_b32_e32 v147, 0xffff0000, v58
	v_rcp_f32_e32 v128, v65
	v_add_f32_e32 v65, 1.0, v97
	s_waitcnt lgkmcnt(0)
	v_pk_fma_f32 v[140:141], v[106:107], v[146:147], v[140:141]
	v_rcp_f32_e32 v129, v65
	v_mul_f32_e32 v65, 0xbfb8aa3b, v140
	v_lshlrev_b32_e32 v136, 16, v51
	v_and_b32_e32 v137, 0xffff0000, v51
	v_exp_f32_e32 v65, v65
	v_mul_f32_e32 v77, 0xbfb8aa3b, v141
	v_lshlrev_b32_e32 v132, 16, v47
	v_and_b32_e32 v133, 0xffff0000, v47
	v_pk_mul_f32 v[138:139], v[88:89], v[136:137]
	v_exp_f32_e32 v77, v77
	v_pk_fma_f32 v[138:139], v[70:71], v[132:133], v[138:139]
	v_lshlrev_b32_e32 v144, 16, v55
	v_and_b32_e32 v145, 0xffff0000, v55
	v_pk_fma_f32 v[138:139], v[100:101], v[144:145], v[138:139]
	v_lshlrev_b32_e32 v148, 16, v59
	v_and_b32_e32 v149, 0xffff0000, v59
	v_pk_fma_f32 v[138:139], v[108:109], v[148:149], v[138:139]
	v_add_f32_e32 v65, 1.0, v65
	v_rcp_f32_e32 v146, v65
	v_add_f32_e32 v65, 1.0, v77
	v_mul_f32_e32 v77, 0xbfb8aa3b, v138
	v_exp_f32_e32 v77, v77
	v_mul_f32_e32 v97, 0xbfb8aa3b, v139
	v_exp_f32_e32 v97, v97
	v_rcp_f32_e32 v147, v65
	v_add_f32_e32 v65, 1.0, v77
	v_rcp_f32_e32 v148, v65
	v_add_f32_e32 v65, 1.0, v97
	v_rcp_f32_e32 v149, v65
	v_pk_mul_f32 v[124:125], v[124:125], v[128:129]
	v_pk_mul_f32 v[82:83], v[82:83], v[110:111]
	v_pk_mul_f32 v[122:123], v[122:123], v[126:127]
	v_pk_mul_f32 v[128:129], v[138:139], v[148:149]
	v_lshlrev_b32_e32 v138, 16, v44
	v_and_b32_e32 v139, 0xffff0000, v44
	v_pk_fma_f32 v[78:79], v[78:79], v[138:139], v[82:83]
	v_pk_mul_f32 v[126:127], v[140:141], v[146:147]
	v_pk_fma_f32 v[78:79], v[90:91], v[114:115], v[78:79]
	v_lshlrev_b32_e32 v140, 16, v45
	v_pk_fma_f32 v[78:79], v[102:103], v[118:119], v[78:79]
	v_and_b32_e32 v141, 0xffff0000, v45
	v_mul_f32_e32 v65, 0xbfb8aa3b, v78
	v_exp_f32_e32 v65, v65
	v_mul_f32_e32 v77, 0xbfb8aa3b, v79
	v_pk_mul_f32 v[84:85], v[84:85], v[112:113]
	v_exp_f32_e32 v77, v77
	v_pk_fma_f32 v[80:81], v[80:81], v[140:141], v[84:85]
	v_add_f32_e32 v65, 1.0, v65
	v_pk_fma_f32 v[80:81], v[92:93], v[116:117], v[80:81]
	v_rcp_f32_e32 v82, v65
	v_pk_fma_f32 v[80:81], v[104:105], v[120:121], v[80:81]
	v_add_f32_e32 v65, 1.0, v77
	v_mul_f32_e32 v77, 0xbfb8aa3b, v80
	v_exp_f32_e32 v77, v77
	v_mul_f32_e32 v83, 0xbfb8aa3b, v81
	v_exp_f32_e32 v85, v83
	v_lshlrev_b32_e32 v90, 16, v42
	v_and_b32_e32 v91, 0xffff0000, v42
	v_pk_mul_f32 v[86:87], v[86:87], v[130:131]
	v_rcp_f32_e32 v83, v65
	v_pk_fma_f32 v[68:69], v[68:69], v[90:91], v[86:87]
	v_add_f32_e32 v65, 1.0, v77
	v_pk_fma_f32 v[68:69], v[98:99], v[134:135], v[68:69]
	v_rcp_f32_e32 v84, v65
	v_add_f32_e32 v65, 1.0, v85
	v_pk_fma_f32 v[68:69], v[106:107], v[142:143], v[68:69]
	v_rcp_f32_e32 v85, v65
	v_mul_f32_e32 v65, 0xbfb8aa3b, v68
	v_exp_f32_e32 v65, v65
	v_mul_f32_e32 v77, 0xbfb8aa3b, v69
	v_lshlrev_b32_e32 v92, 16, v43
	v_and_b32_e32 v93, 0xffff0000, v43
	v_pk_mul_f32 v[88:89], v[88:89], v[132:133]
	v_exp_f32_e32 v77, v77
	v_pk_fma_f32 v[70:71], v[70:71], v[92:93], v[88:89]
	v_add_f32_e32 v65, 1.0, v65
	v_pk_fma_f32 v[70:71], v[100:101], v[136:137], v[70:71]
	v_rcp_f32_e32 v86, v65
	v_pk_fma_f32 v[70:71], v[108:109], v[144:145], v[70:71]
	v_add_f32_e32 v65, 1.0, v77
	v_mul_f32_e32 v77, 0xbfb8aa3b, v70
	v_exp_f32_e32 v77, v77
	v_mul_f32_e32 v87, 0xbfb8aa3b, v71
	v_exp_f32_e32 v89, v87
	v_rcp_f32_e32 v87, v65
	v_add_f32_e32 v65, 1.0, v77
	v_rcp_f32_e32 v88, v65
	v_add_f32_e32 v65, 1.0, v89
	v_rcp_f32_e32 v89, v65
	v_pk_mul_f32 v[78:79], v[78:79], v[82:83]
	v_pk_mul_f32 v[80:81], v[80:81], v[84:85]
	v_pk_mul_f32 v[68:69], v[68:69], v[86:87]
	v_pk_mul_f32 v[70:71], v[70:71], v[88:89]
	v_cvt_pk_bf16_f32 v68, v68, v69
	v_cvt_pk_bf16_f32 v69, v70, v71
	v_cvt_pk_bf16_f32 v70, v78, v79
	v_cvt_pk_bf16_f32 v71, v80, v81
	v_add_u32_e32 v65, v64, v75
	s_add_i32 s90, s90, s34
	ds_write_b128 v65, v[68:71]
	v_cvt_pk_bf16_f32 v68, v126, v127
	v_cvt_pk_bf16_f32 v69, v128, v129
	v_cvt_pk_bf16_f32 v70, v122, v123
	v_cvt_pk_bf16_f32 v71, v124, v125
	v_add_u32_e32 v64, v64, v76
	s_cmp_gt_i32 s90, s98
	ds_write_b128 v64, v[68:71]
	s_cselect_b64 s[48:49], -1, 0
	s_cmp_le_i32 s90, s98
	s_cselect_b32 s42, s90, -1
	v_readfirstlane_b32 s91, v96
	s_cmp_lt_i32 s42, 0
	v_mov_b32_e32 v97, v66
	s_cbranch_scc1 .LBB0_564
	s_lshl_b64 s[6:7], s[42:43], 16
	s_add_u32 s6, s62, s6
	s_addc_u32 s7, s63, s7
	s_lshr_b32 s92, s42, 2
	s_and_b32 s33, s42, 3
	s_and_b32 s4, s42, 0x1fc
	s_cmp_lg_u32 s4, 0
	s_cselect_b64 s[12:13], -1, 0
	s_add_i32 s4, s92, -1
	s_mul_hi_i32 s8, s4, 0x2400
	s_mulk_i32 s4, 0x2400
	s_add_u32 s4, s28, s4
	s_addc_u32 s9, s29, s8
	s_mul_i32 s8, s33, 0x300
	s_add_u32 s8, s4, s8
	v_lshlrev_b32_e32 v2, 4, v96
	s_addc_u32 s9, s9, 0
	v_and_b32_e32 v62, 0xf0, v2
	v_lshl_add_u64 v[58:59], s[8:9], 0, v[62:63]
	v_cmp_gt_i32_e64 s[10:11], 3, v73
	s_mov_b64 s[8:9], 0
	s_and_saveexec_b64 s[50:51], s[10:11]
	s_xor_b64 s[50:51], exec, s[50:51]
	s_cbranch_execz .LBB0_431
	s_and_b64 vcc, exec, s[12:13]
	s_cbranch_vccz .LBB0_429
	v_mul_lo_u32 v2, v73, s75
	v_ashrrev_i32_e32 v3, 31, v2
	v_lshl_add_u64 v[6:7], v[2:3], 1, v[58:59]
	s_mov_b64 s[8:9], -1
	s_branch .LBB0_430

; __device__ __forceinline__ unsigned long long rt() { return __builtin_amdgcn_s_memrealtime(); }
; #define BOTH(k) (IN(k) && (k) + 1 < hi)
; #define GRID_BAR() xcd_barrier(bar)
; __global__ void __launch_bounds__(NWAVES * 64, 2) fwd(Args args) {
;     ...
;             for (int u = (int)blockIdx.x; u < 1024; u += G) p2_dn_unit(lds, u, DNR, HALO, args.in[3], GBT, OLD, DEC + 1024 * 128, BNB, tid, lane, wave, R, (u + G < 1024) ? u + G : -1);
;             if (PROBE_AMP == 22) { __syncthreads(); const unsigned long long t1_ = rt(); while (rt() - t1_ < t1_ - amp_t1_2) __builtin_amdgcn_s_sleep(8); __syncthreads(); }
;         }
;         if (BOTH(2)) GRID_BAR();
.LBB0_610:
	v_readlane_b32 s90, v240, 3
	v_readlane_b32 s66, v240, 24
	v_readlane_b32 s48, v240, 2
	s_mov_b32 s84, s93
	v_readlane_b32 s2, v240, 40
	v_readlane_b32 s34, v240, 41
	s_nop 0
	s_cmp_gt_i32 s57, 3
	s_cbranch_scc0 .LBB0_660

; __global__ void __launch_bounds__(NWAVES * 64, 2) fwd(Args args) {
;     ...
;         if (tid == 0) MISC[10] = (whole && __hip_atomic_load((unsigned*)(ctl + CW_NONLOCAL), RLX_AGENT) == 0u) ? 1u : 0u;
.Lxb3_done:
	s_waitcnt vmcnt(0)
	v_readlane_b32 s8, v240, 6
	v_readlane_b32 s9, v240, 7
	v_mov_b32_e32 v1, 0
	s_nop 1
	s_andn2_b64 vcc, exec, s[8:9]
	s_cbranch_vccnz .Lts1_m10
	v_mov_b32_e32 v1, 0x28000
	global_load_dword v1, v1, s[60:61] offset:2048 sc1
	s_waitcnt vmcnt(0)
	v_cmp_eq_u32_e32 vcc, 0, v1
	s_nop 1
	v_cndmask_b32_e64 v1, 0, 1, vcc
.Lts1_m10:
	v_mov_b32_e32 v2, 0x22968
	ds_write_b32 v2, v1
